# slc: tile loop decoupled with LDS ready/done counters (3 K/V buffers, drift up to 2 tiles) on top of fast tile + top-k early exit
# speedup vs baseline: 1.0062x; 1.0062x over previous
.LBB0_1528:
	s_or_b64 exec, exec, s[10:11]
	v_readlane_b32 s0, v232, 19
	v_readlane_b32 s1, v232, 20
	s_and_b64 vcc, exec, s[0:1]
	s_waitcnt lgkmcnt(0)
	s_barrier
	s_cbranch_vccnz .LBB0_1553
	s_mov_b32 s77, 0
	s_add_u32 s12, s52, 0x12100000
	s_addc_u32 s13, s53, 0
	s_add_u32 s8, s52, 0x16100000
	s_addc_u32 s9, s53, 0
	s_add_u32 s14, s52, 0x17600000
	s_addc_u32 s15, s53, 0
	s_add_u32 s4, s52, 0xe100000
	s_addc_u32 s5, s53, 0
	s_add_u32 s6, s52, 0xf100000
	s_addc_u32 s7, s53, 0
	v_mbcnt_hi_u32_b32 v157, -1, v137
	s_add_u32 s16, s52, 0x24270000
	v_and_b32_e32 v0, 64, v157
	s_addc_u32 s17, s53, 0
	s_mov_b32 s19, 0
	v_mov_b32_e32 v135, 0
	s_movk_i32 s26, 0xc0
	v_mov_b64_e32 v[138:139], s[8:9]
	s_movk_i32 s27, 0x1000
	s_movk_i32 s39, 0x120
	s_mov_b32 s44, 0xf149f2ca
	s_mov_b64 s[20:21], 0x4000
	v_xor_b32_e32 v159, 4, v157
	v_add_u32_e32 v161, 64, v0
	v_xor_b32_e32 v163, 8, v157
	v_mov_b32_e32 v164, 0xf149f2ca
	v_mov_b32_e32 v165, 0x7149f2ca
	s_mov_b32 s45, s2
	s_branch .LBB0_1531

.LBB0_1531:
	s_lshl_b32 s8, s45, 4
	s_and_b32 s8, s8, 0x70
	s_bfe_u32 s9, s45, 0x40003
	s_or_b32 s8, s8, s9
	s_and_b32 s9, s45, 0x100
	s_xor_b32 s10, s8, 0x7f
	s_cmp_eq_u32 s9, 0
	s_cselect_b32 s46, s8, s10
	s_ashr_i32 s54, s45, 9
	s_bfe_u32 s56, s45, 0x20007
	s_lshl_b32 s8, s54, 2
	s_or_b32 s8, s8, s56
	s_ashr_i32 s9, s8, 31
	s_lshl_b32 s47, s46, 6
	s_lshl_b64 s[8:9], s[8:9], 21
	s_add_u32 s10, s4, s8
	v_mov_b32_e32 v24, v136
	s_addc_u32 s11, s5, s9
	s_add_u32 s22, s6, s8
	v_readfirstlane_b32 s18, v24
	s_addc_u32 s23, s7, s9
	s_ashr_i32 s18, s18, 4
	s_and_b32 s18, s18, -4
	v_lshrrev_b32_e32 v0, 2, v24
	s_add_i32 s18, s47, s18
	v_and_or_b32 v140, v0, 3, s18
	s_ashr_i32 s55, s54, 31
	s_lshl_b64 s[54:55], s[54:55], 13
	v_ashrrev_i32_e32 v141, 31, v140
	v_lshl_add_u64 v[12:13], s[54:55], 0, v[140:141]
	v_and_b32_e32 v6, 3, v24
	v_lshl_add_u64 v[14:15], v[12:13], 0, 32
	v_lshlrev_b64 v[0:1], 12, v[12:13]
	v_lshl_or_b32 v25, s56, 2, v6
	v_lshlrev_b64 v[2:3], 12, v[14:15]
	v_mad_u64_u32 v[4:5], s[54:55], v12, s26, v[138:139]
	v_lshl_add_u64 v[0:1], s[12:13], 0, v[0:1]
	v_lshlrev_b32_e32 v134, 8, v25
	v_lshl_add_u64 v[2:3], s[12:13], 0, v[2:3]
	v_mad_i32_i24 v5, v13, s26, v5
	s_lshl_b32 s18, s56, 4
	v_lshl_add_u64 v[0:1], v[0:1], 0, v[134:135]
	v_lshl_add_u64 v[2:3], v[2:3], 0, v[134:135]
	v_lshl_add_u64 v[4:5], v[4:5], 0, s[18:19]
	v_lshlrev_b32_e32 v134, 2, v6
	v_lshlrev_b64 v[6:7], 6, v[12:13]
	v_lshl_add_u64 v[4:5], v[4:5], 0, v[134:135]
	v_lshl_add_u64 v[6:7], s[16:17], 0, v[6:7]
	v_lshlrev_b64 v[8:9], 6, v[14:15]
	v_lshl_add_u64 v[6:7], v[6:7], 0, s[18:19]
	v_lshl_add_u64 v[8:9], s[16:17], 0, v[8:9]
	v_add_co_u32_e32 v10, vcc, s27, v4
	v_lshl_add_u64 v[8:9], v[8:9], 0, s[18:19]
	s_nop 0
	v_addc_co_u32_e32 v11, vcc, 0, v5, vcc
	global_load_dwordx4 v[62:65], v[6:7], off
	global_load_dword v167, v[4:5], off offset:64
	global_load_dwordx4 v[66:69], v[8:9], off
	global_load_dword v166, v[10:11], off offset:2112
	v_mov_b32_e32 v143, v135
	v_and_b32_e32 v142, 48, v24
	v_lshlrev_b32_e32 v4, 4, v24
	v_ashrrev_i32_e32 v16, 4, v24
	v_add_u32_e32 v5, 0x200, v24
	v_lshl_add_u64 v[0:1], v[0:1], 0, v[142:143]
	v_ashrrev_i32_e32 v17, 31, v16
	v_ashrrev_i32_e32 v18, 4, v5
	global_load_dwordx4 v[70:73], v[0:1], off
	global_load_dwordx4 v[74:77], v[0:1], off offset:64
	global_load_dwordx4 v[78:81], v[0:1], off offset:128
	global_load_dwordx4 v[82:85], v[0:1], off offset:192
	v_lshl_add_u64 v[0:1], v[2:3], 0, v[142:143]
	v_and_b32_e32 v134, 0xf0, v4
	v_lshlrev_b64 v[20:21], 8, v[16:17]
	v_ashrrev_i32_e32 v19, 31, v18
	global_load_dwordx4 v[86:89], v[0:1], off
	global_load_dwordx4 v[90:93], v[0:1], off offset:64
	global_load_dwordx4 v[94:97], v[0:1], off offset:128
	global_load_dwordx4 v[98:101], v[0:1], off offset:192
	v_lshl_add_u64 v[0:1], s[10:11], 0, v[134:135]
	v_lshlrev_b64 v[22:23], 8, v[18:19]
	v_lshl_add_u64 v[2:3], s[22:23], 0, v[134:135]
	v_lshl_add_u64 v[4:5], v[0:1], 0, v[20:21]
	v_lshl_add_u64 v[6:7], v[2:3], 0, v[20:21]
	v_lshl_add_u64 v[0:1], v[0:1], 0, v[22:23]
	v_lshl_add_u64 v[2:3], v[2:3], 0, v[22:23]
	v_cmp_lt_i32_e32 vcc, v159, v161
	v_lshrrev_b32_e32 v170, 2, v142
	s_add_i32 s47, s47, 64
	v_cndmask_b32_e32 v26, v157, v159, vcc
	v_cmp_lt_i32_e32 vcc, v163, v161
	v_lshlrev_b32_e32 v17, 2, v26
	v_lshlrev_b32_e32 v26, 3, v24
	v_cndmask_b32_e32 v27, v157, v163, vcc
	v_lshlrev_b32_e32 v19, 2, v27
	v_and_b32_e32 v27, 15, v24
	v_bfe_u32 v24, v24, 2, 2
	v_mul_lo_u32 v171, v16, s39
	v_or_b32_e32 v16, v170, v24
	s_add_u32 s8, s52, s8
	v_mul_u32_u24_e32 v175, 0x120, v16
	v_sub_u32_e32 v16, v140, v170
	s_addc_u32 s9, s53, s9
	v_mul_lo_u32 v174, v18, s39
	v_add_u32_e32 v177, 32, v16
	v_add_u32_e32 v178, 30, v16
	v_add_u32_e32 v179, 29, v16
	v_add_u32_e32 v180, 16, v16
	v_add_u32_e32 v181, 14, v16
	v_add_u32_e32 v182, 13, v16
	v_lshl_add_u64 v[152:153], s[8:9], 0, v[20:21]
	v_lshl_add_u64 v[154:155], s[8:9], 0, v[22:23]
	v_mul_u32_u24_e32 v172, 0x120, v27
	v_and_b32_e32 v173, 24, v26
	v_lshlrev_b32_e32 v148, 7, v25
	v_add_u32_e32 v183, 16, v134
	v_lshlrev_b32_e32 v134, 4, v27
	v_mov_b32_e32 v8, v135
	v_mov_b32_e32 v9, v135
	v_mov_b32_e32 v10, v135
	v_mov_b32_e32 v11, v135
	v_lshlrev_b64 v[150:151], 11, v[12:13]
	v_add_u32_e32 v12, v183, v171
	v_add_u32_e32 v13, v183, v174
	v_mov_b64_e32 v[38:39], v[10:11]
	v_mov_b64_e32 v[42:43], v[10:11]
	v_mov_b64_e32 v[46:47], v[10:11]
	v_mov_b64_e32 v[50:51], v[10:11]
	v_mov_b64_e32 v[54:55], v[10:11]
	v_mov_b64_e32 v[58:59], v[10:11]
	v_mov_b64_e32 v[34:35], v[10:11]
	v_mov_b32_e32 v184, 0xc6ea6000
	s_mov_b32 s18, 0
	v_mov_b64_e32 v[36:37], v[8:9]
	v_mov_b64_e32 v[40:41], v[8:9]
	v_mov_b64_e32 v[44:45], v[8:9]
	v_mov_b64_e32 v[48:49], v[8:9]
	v_mov_b64_e32 v[52:53], v[8:9]
	v_mov_b64_e32 v[56:57], v[8:9]
	v_xad_u32 v176, v170, 15, v140
	v_mov_b64_e32 v[32:33], v[8:9]
	s_waitcnt vmcnt(11)
	v_mov_b64_e32 v[144:145], v[62:63]
	v_mov_b64_e32 v[62:63], v[10:11]
	s_waitcnt vmcnt(9)
	v_mov_b64_e32 v[146:147], v[68:69]
	s_waitcnt vmcnt(8)
	global_load_dwordx4 v[102:105], v[4:5], off
	global_load_dwordx4 v[106:109], v[6:7], off
	global_load_dwordx4 v[110:113], v[0:1], off
	global_load_dwordx4 v[114:117], v[2:3], off
	v_lshlrev_b64 v[68:69], 11, v[14:15]
	ds_bpermute_b32 v14, v17, v144
	ds_bpermute_b32 v15, v17, v145
	ds_bpermute_b32 v16, v17, v64
	ds_bpermute_b32 v18, v17, v65
	ds_bpermute_b32 v20, v17, v66
	ds_bpermute_b32 v21, v17, v67
	ds_bpermute_b32 v22, v17, v146
	ds_bpermute_b32 v17, v17, v147
	s_waitcnt lgkmcnt(6)
	v_or_b32_e32 v15, v15, v145
	v_or_b32_e32 v14, v14, v144
	s_waitcnt lgkmcnt(4)
	v_or_b32_e32 v18, v18, v65
	v_or_b32_e32 v16, v16, v64
	s_waitcnt lgkmcnt(2)
	v_or_b32_e32 v21, v21, v67
	v_or_b32_e32 v20, v20, v66
	s_waitcnt lgkmcnt(0)
	v_or_b32_e32 v17, v17, v147
	v_or_b32_e32 v22, v22, v146
	ds_bpermute_b32 v23, v19, v14
	ds_bpermute_b32 v24, v19, v15
	ds_bpermute_b32 v25, v19, v16
	ds_bpermute_b32 v26, v19, v18
	ds_bpermute_b32 v27, v19, v20
	ds_bpermute_b32 v28, v19, v21
	ds_bpermute_b32 v29, v19, v22
	ds_bpermute_b32 v19, v19, v17
	v_mov_b64_e32 v[0:1], v[8:9]
	v_mov_b64_e32 v[4:5], v[8:9]
	s_waitcnt lgkmcnt(6)
	v_or_b32_e32 v137, v24, v15
	v_or_b32_e32 v156, v23, v14
	s_waitcnt lgkmcnt(4)
	v_or_b32_e32 v141, v26, v18
	v_or_b32_e32 v158, v25, v16
	s_waitcnt lgkmcnt(2)
	v_or_b32_e32 v143, v28, v21
	v_or_b32_e32 v160, v27, v20
	s_waitcnt lgkmcnt(0)
	v_or_b32_e32 v149, v19, v17
	v_or_b32_e32 v162, v29, v22
	v_readfirstlane_b32 s60, v156
	v_readfirstlane_b32 s61, v137
	v_readfirstlane_b32 s62, v158
	v_readfirstlane_b32 s63, v141
	v_readfirstlane_b32 s64, v160
	v_readfirstlane_b32 s65, v143
	v_readfirstlane_b32 s67, v149
	v_readfirstlane_b32 s66, v162
	v_mov_b64_e32 v[18:19], v[10:11]
	v_mov_b64_e32 v[22:23], v[10:11]
	v_mov_b64_e32 v[26:27], v[10:11]
	v_mov_b64_e32 v[30:31], v[10:11]
	v_mov_b64_e32 v[60:61], v[8:9]
	v_mov_b64_e32 v[2:3], v[10:11]
	v_mov_b64_e32 v[6:7], v[10:11]
	v_mov_b64_e32 v[16:17], v[8:9]
	v_mov_b64_e32 v[20:21], v[8:9]
	v_mov_b64_e32 v[24:25], v[8:9]
	s_waitcnt vmcnt(3)
	ds_write_b128 v12, v[102:105]
	s_waitcnt vmcnt(2)
	ds_write_b128 v12, v[106:109] offset:18432
	s_waitcnt vmcnt(1)
	ds_write_b128 v13, v[110:113]
	s_waitcnt vmcnt(0)
	ds_write_b128 v13, v[114:117] offset:18432
	v_mov_b64_e32 v[14:15], v[10:11]
	v_mov_b64_e32 v[12:13], v[8:9]
	v_mov_b64_e32 v[28:29], v[8:9]
	v_mov_b32_e32 v169, v135
	v_mov_b32_e32 v168, v135
	v_mov_b32_e32 v185, 0xc6ea6000
	s_mov_b32 s54, 0
	s_mov_b32 s80, 0x1b100
	v_lshl_add_u32 v229, v136, 2, s80
	ds_write_b32 v229, v135
	s_waitcnt lgkmcnt(0)
	s_barrier
	s_branch .Las_pre
.LBB0_1535:
	s_cmp_gt_u32 s54, 63
	s_cselect_b64 s[8:9], -1, 0
	v_cndmask_b32_e64 v118, v137, v141, s[8:9]
	v_cndmask_b32_e64 v120, v156, v158, s[8:9]
	s_lshl_b64 s[56:57], 1, s54
	v_and_b32_e32 v119, s57, v118
	v_and_b32_e32 v118, s56, v120
	v_cmp_ne_u64_e32 vcc, 0, v[118:119]
	v_add3_u32 v187, s55, v142, v172
	v_cndmask_b32_e64 v186, 0, 1, s[22:23]
	s_cbranch_vccz .LBB0_1541
	ds_read_b128 v[118:121], v187
	ds_read_b128 v[122:125], v187 offset:64
	ds_read_b128 v[126:129], v187 offset:4608
	ds_read_b128 v[130:133], v187 offset:4672
	v_cndmask_b32_e64 v196, v145, v65, s[8:9]
	v_cndmask_b32_e64 v206, v144, v64, s[8:9]
	s_waitcnt lgkmcnt(3)
	v_mfma_f32_16x16x32_bf16 v[118:121], v[118:121], v[70:73], 0
	v_and_b32_e32 v197, s57, v196
	v_and_b32_e32 v196, s56, v206
	v_readfirstlane_b32 s58, v186
	s_waitcnt lgkmcnt(2)
	v_mfma_f32_16x16x32_bf16 v[198:201], v[122:125], v[74:77], v[118:121]
	v_cmp_eq_u64_e64 s[10:11], 0, v[196:197]
	s_bitcmp0_b32 s58, 0
	s_mov_b64 s[58:59], -1
	ds_read_b128 v[118:121], v187 offset:4736
	s_waitcnt lgkmcnt(2)
	v_mfma_f32_16x16x32_bf16 v[126:129], v[126:129], v[70:73], 0
	s_waitcnt lgkmcnt(1)
	v_mfma_f32_16x16x32_bf16 v[122:125], v[130:133], v[74:77], v[126:129]
	s_nop 5
	ds_read_b128 v[126:129], v187 offset:9216
	ds_read_b128 v[130:133], v187 offset:4800
	s_waitcnt lgkmcnt(2)
	v_mfma_f32_16x16x32_bf16 v[202:205], v[118:121], v[78:81], v[122:125]
	ds_read_b128 v[118:121], v187 offset:9280
	s_waitcnt lgkmcnt(2)
	v_mfma_f32_16x16x32_bf16 v[122:125], v[126:129], v[70:73], 0
	ds_read_b128 v[126:129], v187 offset:9344
	s_waitcnt lgkmcnt(1)
	v_mfma_f32_16x16x32_bf16 v[118:121], v[118:121], v[74:77], v[122:125]
	s_nop 4
	ds_read_b128 v[122:125], v187 offset:13824
	ds_read_b128 v[192:195], v187 offset:9408
	ds_read_b128 v[188:191], v187 offset:13888
	ds_read_b128 v[206:209], v187 offset:14016
	s_waitcnt lgkmcnt(4)
	v_mfma_f32_16x16x32_bf16 v[126:129], v[126:129], v[78:81], v[118:121]
	s_nop 2
	ds_read_b128 v[118:121], v187 offset:13952
	s_waitcnt lgkmcnt(4)
	v_mfma_f32_16x16x32_bf16 v[122:125], v[122:125], v[70:73], 0
	ds_read_b128 v[210:213], v187 offset:128
	ds_read_b128 v[214:217], v187 offset:192
	s_waitcnt lgkmcnt(4)
	v_mfma_f32_16x16x32_bf16 v[122:125], v[188:191], v[74:77], v[122:125]
	s_waitcnt lgkmcnt(2)
	v_mfma_f32_16x16x32_bf16 v[118:121], v[118:121], v[78:81], v[122:125]
	v_mfma_f32_16x16x32_bf16 v[122:125], v[192:195], v[82:85], v[126:129]
	v_mfma_f32_16x16x32_bf16 v[126:129], v[130:133], v[82:85], v[202:205]
	s_waitcnt lgkmcnt(1)
	v_mfma_f32_16x16x32_bf16 v[130:133], v[210:213], v[78:81], v[198:201]
	s_nop 4
	v_mov_b32_e32 v192, v125
	v_mov_b32_e32 v194, v124
	v_mov_b32_e32 v195, v123
	v_mfma_f32_16x16x32_bf16 v[118:121], v[206:209], v[82:85], v[118:121]
	v_mov_b32_e32 v193, v122
	v_mov_b32_e32 v196, v129
	v_mov_b32_e32 v200, v128
	s_waitcnt lgkmcnt(0)
	v_mfma_f32_16x16x32_bf16 v[130:133], v[214:217], v[82:85], v[130:133]
	v_mov_b32_e32 v197, v127
	s_nop 1
	v_mov_b32_e32 v190, v121
	v_mov_b32_e32 v191, v120
	v_mov_b32_e32 v188, v119
	v_mov_b32_e32 v189, v118
	v_mov_b32_e32 v198, v126
	v_mov_b32_e32 v199, v133
	v_mov_b32_e32 v202, v132
	v_mov_b32_e32 v201, v131
	v_mov_b32_e32 v203, v130
	s_cbranch_scc1 .LBB0_1549
	s_andn2_b64 vcc, exec, s[58:59]
	s_cbranch_vccz .LBB0_1550

.LBB0_1546:
	v_cndmask_b32_e64 v202, v185, v165, s[8:9]
	v_sub_f32_e32 v119, v200, v202
	v_sub_f32_e32 v120, v199, v202
	v_exp_f32_e32 v199, v119
	v_sub_f32_e32 v119, v198, v202
	v_exp_f32_e32 v198, v119
	v_sub_f32_e32 v119, v197, v202
	v_exp_f32_e32 v203, v119
	v_sub_f32_e32 v119, v196, v202
	v_exp_f32_e32 v204, v119
	v_sub_f32_e32 v119, v195, v202
	v_sub_f32_e32 v118, v201, v202
	v_exp_f32_e32 v205, v119
	v_sub_f32_e32 v119, v194, v202
	v_add3_u32 v207, s55, v175, v173
	v_exp_f32_e32 v118, v118
	v_exp_f32_e32 v201, v120
	v_exp_f32_e32 v206, v119
	ds_read_b64_tr_b16 v[124:125], v207 offset:23040
	ds_read_b64_tr_b16 v[122:123], v207 offset:18432
	v_add_f32_e32 v200, 0, v118
	v_cvt_pk_bf16_f32 v118, v118, v199
	v_cvt_pk_bf16_f32 v119, v201, v198
	v_cvt_pk_bf16_f32 v120, v203, v204
	v_cvt_pk_bf16_f32 v121, v205, v206
	ds_read_b64_tr_b16 v[128:129], v207 offset:23072
	ds_read_b64_tr_b16 v[126:127], v207 offset:18464
	ds_read_b64_tr_b16 v[130:131], v207 offset:18496
	ds_read_b64_tr_b16 v[194:195], v207 offset:18528
	ds_read_b64_tr_b16 v[132:133], v207 offset:23104
	ds_read_b64_tr_b16 v[196:197], v207 offset:23136
	s_waitcnt lgkmcnt(6)
	v_mfma_f32_16x16x32_bf16 v[32:35], v[122:125], v[118:121], v[32:35]
	v_sub_f32_e32 v122, v193, v202
	v_exp_f32_e32 v208, v122
	v_sub_f32_e32 v122, v192, v202
	v_exp_f32_e32 v209, v122
	v_sub_f32_e32 v122, v191, v202
	v_exp_f32_e32 v210, v122
	ds_read_b64_tr_b16 v[122:123], v207 offset:18560
	ds_read_b64_tr_b16 v[124:125], v207 offset:23168
	s_waitcnt lgkmcnt(0)
	v_mfma_f32_16x16x32_bf16 v[16:19], v[122:125], v[118:121], v[16:19]
	v_sub_f32_e32 v122, v187, v202
	v_sub_f32_e32 v211, v190, v202
	v_mfma_f32_16x16x32_bf16 v[20:23], v[194:197], v[118:121], v[20:23]
	v_exp_f32_e32 v195, v122
	v_sub_f32_e32 v122, v186, v202
	v_exp_f32_e32 v196, v122
	v_sub_f32_e32 v122, v189, v202
	v_mfma_f32_16x16x32_bf16 v[28:31], v[126:129], v[118:121], v[28:31]
	v_exp_f32_e32 v197, v122
	v_sub_f32_e32 v122, v188, v202
	v_exp_f32_e32 v194, v211
	v_mfma_f32_16x16x32_bf16 v[24:27], v[130:133], v[118:121], v[24:27]
	ds_read_b64_tr_b16 v[128:129], v207 offset:23200
	ds_read_b64_tr_b16 v[126:127], v207 offset:18592
	ds_read_b64_tr_b16 v[130:131], v207 offset:18624
	ds_read_b64_tr_b16 v[190:191], v207 offset:18656
	ds_read_b64_tr_b16 v[132:133], v207 offset:23232
	ds_read_b64_tr_b16 v[192:193], v207 offset:23264
	v_exp_f32_e32 v202, v122
	ds_read_b64_tr_b16 v[122:123], v207 offset:27648
	ds_read_b64_tr_b16 v[124:125], v207 offset:32256
	s_waitcnt lgkmcnt(6)
	v_mfma_f32_16x16x32_bf16 v[12:15], v[126:129], v[118:121], v[12:15]
	s_waitcnt lgkmcnt(3)
	v_mfma_f32_16x16x32_bf16 v[4:7], v[130:133], v[118:121], v[4:7]
	ds_read_b64_tr_b16 v[128:129], v207 offset:32288
	ds_read_b64_tr_b16 v[126:127], v207 offset:27680
	ds_read_b64_tr_b16 v[130:131], v207 offset:27712
	ds_read_b64_tr_b16 v[186:187], v207 offset:27744
	ds_read_b64_tr_b16 v[132:133], v207 offset:32320
	ds_read_b64_tr_b16 v[188:189], v207 offset:32352
	s_waitcnt lgkmcnt(8)
	v_mfma_f32_16x16x32_bf16 v[0:3], v[190:193], v[118:121], v[0:3]
	v_cvt_pk_bf16_f32 v118, v208, v209
	v_cvt_pk_bf16_f32 v119, v210, v194
	v_cvt_pk_bf16_f32 v120, v195, v196
	v_cvt_pk_bf16_f32 v121, v197, v202
	s_waitcnt lgkmcnt(6)
	s_nop 0
	v_mfma_f32_16x16x32_bf16 v[32:35], v[122:125], v[118:121], v[32:35]
	v_add_f32_e32 v122, v199, v200
	v_add_f32_e32 v122, v201, v122
	v_add_f32_e32 v122, v198, v122
	v_add_f32_e32 v122, v203, v122
	v_add_f32_e32 v122, v204, v122
	s_waitcnt lgkmcnt(4)
	v_mfma_f32_16x16x32_bf16 v[28:31], v[126:129], v[118:121], v[28:31]
	v_add_f32_e32 v126, v205, v122
	ds_read_b64_tr_b16 v[122:123], v207 offset:27776
	ds_read_b64_tr_b16 v[124:125], v207 offset:32384
	v_add_f32_e32 v190, v206, v126
	s_waitcnt lgkmcnt(3)
	v_mfma_f32_16x16x32_bf16 v[24:27], v[130:133], v[118:121], v[24:27]
	s_waitcnt lgkmcnt(2)
	v_mfma_f32_16x16x32_bf16 v[20:23], v[186:189], v[118:121], v[20:23]
	ds_read_b64_tr_b16 v[128:129], v207 offset:32416
	ds_read_b64_tr_b16 v[126:127], v207 offset:27808
	ds_read_b64_tr_b16 v[130:131], v207 offset:27840
	ds_read_b64_tr_b16 v[186:187], v207 offset:27872
	ds_read_b64_tr_b16 v[132:133], v207 offset:32448
	ds_read_b64_tr_b16 v[188:189], v207 offset:32480
	s_waitcnt lgkmcnt(6)
	v_mfma_f32_16x16x32_bf16 v[16:19], v[122:125], v[118:121], v[16:19]
	v_add_f32_e32 v122, v208, v190
	v_add_f32_e32 v122, v209, v122
	v_add_f32_e32 v122, v210, v122
	v_add_f32_e32 v122, v194, v122
	v_add_f32_e32 v122, v195, v122
	s_waitcnt lgkmcnt(4)
	v_mfma_f32_16x16x32_bf16 v[12:15], v[126:129], v[118:121], v[12:15]
	v_add_f32_e32 v122, v196, v122
	v_add_f32_e32 v122, v197, v122
	v_add_f32_e32 v122, v202, v122
	s_waitcnt lgkmcnt(1)
	v_mfma_f32_16x16x32_bf16 v[4:7], v[130:133], v[118:121], v[4:7]
	v_add_f32_e32 v168, v168, v122
	s_waitcnt lgkmcnt(0)
	v_mfma_f32_16x16x32_bf16 v[0:3], v[186:189], v[118:121], v[0:3]
.LBB0_1547:
	s_branch .Las_s3
.LBB0_1549:
	v_add_u32_e32 v190, s18, v170
	v_cmp_gt_i32_e32 vcc, v190, v140
	s_or_b64 vcc, s[10:11], vcc
	v_add_u32_e32 v189, 2, v190
	v_cndmask_b32_e32 v203, v130, v164, vcc
	v_cmp_lt_i32_e32 vcc, v190, v140
	s_nop 1
	v_cndmask_b32_e32 v188, v164, v131, vcc
	v_cmp_gt_i32_e32 vcc, v189, v140
	s_or_b64 vcc, s[10:11], vcc
	v_add_u32_e32 v189, 3, v190
	v_cndmask_b32_e32 v202, v132, v164, vcc
	v_cmp_gt_i32_e32 vcc, v189, v140
	s_or_b64 vcc, s[10:11], vcc
	v_add_u32_e32 v189, 16, v190
	v_cndmask_b32_e32 v199, v133, v164, vcc
	v_cmp_gt_i32_e32 vcc, v189, v140
	s_or_b64 vcc, s[10:11], vcc
	v_add_u32_e32 v189, 17, v190
	v_cndmask_b32_e32 v198, v126, v164, vcc
	v_cmp_gt_i32_e32 vcc, v189, v140
	s_or_b64 vcc, s[10:11], vcc
	v_add_u32_e32 v189, 18, v190
	v_cndmask_b32_e32 v197, v127, v164, vcc
	v_cmp_gt_i32_e32 vcc, v189, v140
	s_or_b64 vcc, s[10:11], vcc
	v_add_u32_e32 v189, 19, v190
	v_cndmask_b32_e32 v200, v128, v164, vcc
	v_cmp_gt_i32_e32 vcc, v189, v140
	s_or_b64 vcc, s[10:11], vcc
	v_add_u32_e32 v189, 32, v190
	v_cndmask_b32_e32 v196, v129, v164, vcc
	v_cmp_gt_i32_e32 vcc, v189, v140
	s_or_b64 vcc, s[10:11], vcc
	v_add_u32_e32 v189, 33, v190
	v_cndmask_b32_e32 v193, v122, v164, vcc
	v_cmp_gt_i32_e32 vcc, v189, v140
	v_cndmask_b32_e64 v201, v188, v164, s[10:11]
	s_or_b64 vcc, s[10:11], vcc
	v_add_u32_e32 v189, 34, v190
	v_max3_f32 v188, v203, s44, v201
	v_cndmask_b32_e32 v195, v123, v164, vcc
	v_cmp_gt_i32_e32 vcc, v189, v140
	v_max3_f32 v188, v188, v202, v199
	s_or_b64 vcc, s[10:11], vcc
	v_add_u32_e32 v189, 35, v190
	v_max3_f32 v188, v188, v198, v197
	v_cndmask_b32_e32 v194, v124, v164, vcc
	v_cmp_gt_i32_e32 vcc, v189, v140
	v_max3_f32 v188, v188, v200, v196
	s_or_b64 vcc, s[10:11], vcc
	v_max3_f32 v188, v188, v193, v195
	v_cndmask_b32_e32 v192, v125, v164, vcc
	v_max3_f32 v191, v188, v194, v192
	v_add_u32_e32 v188, 48, v190
	v_cmp_gt_i32_e32 vcc, v188, v140
	s_or_b64 vcc, s[10:11], vcc
	v_add_u32_e32 v188, 49, v190
	v_cndmask_b32_e32 v189, v118, v164, vcc
	v_cmp_gt_i32_e32 vcc, v188, v140
	s_or_b64 vcc, s[10:11], vcc
	s_nop 0
	v_cndmask_b32_e32 v188, v119, v164, vcc
	v_max3_f32 v204, v191, v189, v188
	v_add_u32_e32 v191, 50, v190
	v_cmp_gt_i32_e32 vcc, v191, v140
	s_or_b64 vcc, s[10:11], vcc
	v_add_u32_e32 v190, 51, v190
	v_cndmask_b32_e32 v191, v120, v164, vcc
	v_cmp_gt_i32_e32 vcc, v190, v140
	s_or_b64 vcc, s[10:11], vcc
	s_nop 0
	v_cndmask_b32_e32 v190, v121, v164, vcc
	v_max3_f32 v204, v204, v191, v190
	s_cbranch_execnz .LBB0_1538

.Las_pre:
	s_mov_b32 s74, 0
	s_mov_b32 s75, 0x9000
	v_mov_b32_e32 v231, 0x1b100
	v_mov_b32_e32 v230, 1
	s_cmp_lt_u32 0, s46
	s_cbranch_scc0 .Las_loop
	v_lshl_add_u64 v[102:103], v[152:153], 0, v[134:135]
	v_add_co_u32_e32 v104, vcc, 0xe104000, v102
	v_lshl_add_u64 v[110:111], v[154:155], 0, v[134:135]
	v_addc_co_u32_e32 v105, vcc, 0, v103, vcc
	v_add_co_u32_e32 v106, vcc, 0xf104000, v102
	s_nop 1
	v_addc_co_u32_e32 v107, vcc, 0, v103, vcc
	v_add_co_u32_e32 v112, vcc, 0xe104000, v110
	global_load_dwordx4 v[102:105], v[104:105], off
	s_nop 1
	global_load_dwordx4 v[106:109], v[106:107], off
	v_addc_co_u32_e32 v113, vcc, 0, v111, vcc
	v_add_co_u32_e32 v114, vcc, 0xf104000, v110
	s_nop 1
	v_addc_co_u32_e32 v115, vcc, 0, v111, vcc
	global_load_dwordx4 v[110:113], v[112:113], off
	s_nop 0
	global_load_dwordx4 v[114:117], v[114:115], off
.Las_loop:
	s_cmp_lt_u32 s54, s46
	s_cselect_b64 s[22:23], -1, 0
	s_cbranch_scc0 .Las_nostage
	s_cmp_lt_u32 s54, 2
	s_cbranch_scc1 .Las_s1_go
	s_cmp_lg_u32 s77, 0
	s_cbranch_scc1 .Lpoll_done_s1
	s_mov_b32 s78, 0
.Lpoll_s1:
	ds_read_b32 v229, v231 offset:504
	s_waitcnt lgkmcnt(0)
	v_readfirstlane_b32 s79, v229
	s_cmp_ge_u32 s79, 8
	s_cbranch_scc1 .Lpoll_done_s1
	s_sleep 1
	s_add_i32 s78, s78, 1
	s_cmpk_lt_u32 s78, 0x2000
	s_cbranch_scc1 .Lpoll_s1
	s_mov_b32 s77, 1
.Lpoll_done_s1:
.Las_s1_go:
	v_add_u32_e32 v118, s75, v183
	v_add_u32_e32 v119, v118, v174
	v_add_u32_e32 v118, v118, v171
	s_waitcnt vmcnt(3)
	ds_write_b128 v118, v[102:105]
	s_waitcnt vmcnt(2)
	ds_write_b128 v118, v[106:109] offset:18432
	s_waitcnt vmcnt(1)
	ds_write_b128 v119, v[110:113]
	s_waitcnt vmcnt(0)
	ds_write_b128 v119, v[114:117] offset:18432
	s_waitcnt lgkmcnt(0)
	s_mov_b64 exec, 1
	ds_add_u32 v231, v230 offset:4
	s_mov_b64 exec, -1
	s_add_i32 s79, s54, 2
	s_cmp_le_u32 s79, s46
	s_cbranch_scc0 .Las_nostage
	v_lshl_add_u64 v[102:103], v[152:153], 0, v[134:135]
	v_add_co_u32_e32 v104, vcc, 0xe108000, v102
	v_lshl_add_u64 v[110:111], v[154:155], 0, v[134:135]
	v_addc_co_u32_e32 v105, vcc, 0, v103, vcc
	v_add_co_u32_e32 v106, vcc, 0xf108000, v102
	s_nop 1
	v_addc_co_u32_e32 v107, vcc, 0, v103, vcc
	v_add_co_u32_e32 v112, vcc, 0xe108000, v110
	global_load_dwordx4 v[102:105], v[104:105], off
	s_nop 1
	global_load_dwordx4 v[106:109], v[106:107], off
	v_addc_co_u32_e32 v113, vcc, 0, v111, vcc
	v_add_co_u32_e32 v114, vcc, 0xf108000, v110
	s_nop 1
	v_addc_co_u32_e32 v115, vcc, 0, v111, vcc
	global_load_dwordx4 v[110:113], v[112:113], off
	s_nop 0
	global_load_dwordx4 v[114:117], v[114:115], off
.Las_nostage:
	s_add_i32 s55, s74, 16
	s_cmp_eq_u32 s54, 0
	s_cbranch_scc1 .LBB0_1535
	s_cmp_lt_u32 s54, s46
	s_cbranch_scc1 .Las_fast
	s_cmp_lg_u32 s77, 0
	s_cbranch_scc1 .Lpoll_done_slow
	s_mov_b32 s78, 0
.Lpoll_slow:
	ds_read_b32 v229, v231 offset:0
	s_waitcnt lgkmcnt(0)
	v_readfirstlane_b32 s79, v229
	s_cmp_ge_u32 s79, 8
	s_cbranch_scc1 .Lpoll_done_slow
	s_sleep 1
	s_add_i32 s78, s78, 1
	s_cmpk_lt_u32 s78, 0x2000
	s_cbranch_scc1 .Lpoll_slow
	s_mov_b32 s77, 1

.Las_fast:
	s_lshl_b64 s[56:57], 1, s54
	s_cmp_gt_u32 s54, 63
	s_cselect_b64 s[8:9], -1, 0
	s_cselect_b64 s[68:69], s[62:63], s[60:61]
	s_cselect_b64 s[70:71], s[66:67], s[64:65]
	s_and_b64 s[68:69], s[68:69], s[56:57]
	s_and_b64 s[70:71], s[70:71], s[56:57]
	s_or_b64 s[82:83], s[68:69], s[70:71]
	s_cbranch_scc0 .Las_s3
	s_cmp_lg_u32 s77, 0
	s_cbranch_scc1 .Lpoll_done_fast
	s_mov_b32 s78, 0

.Lpoll_done_fast:
	v_add3_u32 v224, s55, v142, v172
	v_add3_u32 v225, s55, v175, v173
	s_cmp_lg_u64 s[68:69], 0
	s_cbranch_scc0 .Lft_done_slcA
	ds_read_b128 v[118:121], v224 offset:0
	ds_read_b128 v[122:125], v224 offset:4608
	ds_read_b128 v[126:129], v224 offset:9216
	ds_read_b128 v[130:133], v224 offset:13824
	ds_read_b128 v[204:207], v224 offset:64
	ds_read_b128 v[208:211], v224 offset:4672
	ds_read_b128 v[212:215], v224 offset:9280
	ds_read_b128 v[216:219], v224 offset:13888
	v_cndmask_b32_e64 v228, v144, v64, s[8:9]
	v_cndmask_b32_e64 v229, v145, v65, s[8:9]
	v_and_b32_e32 v228, s56, v228
	v_and_b32_e32 v229, s57, v229
	v_cmp_ne_u64_e32 vcc, 0, v[228:229]
	s_nop 1
	v_cndmask_b32_e32 v220, v165, v184, vcc
	v_xor_b32_e32 v220, 0x80000000, v220
	v_mov_b32_e32 v221, v220
	v_mov_b32_e32 v222, v220
	v_mov_b32_e32 v223, v220
	s_waitcnt lgkmcnt(4)
	s_nop 0
	v_mfma_f32_16x16x32_bf16 v[188:191], v[118:121], v[70:73], v[220:223]
	v_mfma_f32_16x16x32_bf16 v[192:195], v[122:125], v[70:73], v[220:223]
	v_mfma_f32_16x16x32_bf16 v[196:199], v[126:129], v[70:73], v[220:223]
	v_mfma_f32_16x16x32_bf16 v[200:203], v[130:133], v[70:73], v[220:223]
	ds_read_b128 v[118:121], v224 offset:128
	ds_read_b128 v[122:125], v224 offset:4736
	ds_read_b128 v[126:129], v224 offset:9344
	ds_read_b128 v[130:133], v224 offset:13952
	s_waitcnt lgkmcnt(4)
	v_mfma_f32_16x16x32_bf16 v[188:191], v[204:207], v[74:77], v[188:191]
	v_mfma_f32_16x16x32_bf16 v[192:195], v[208:211], v[74:77], v[192:195]
	v_mfma_f32_16x16x32_bf16 v[196:199], v[212:215], v[74:77], v[196:199]
	v_mfma_f32_16x16x32_bf16 v[200:203], v[216:219], v[74:77], v[200:203]
	ds_read_b128 v[204:207], v224 offset:192
	ds_read_b128 v[208:211], v224 offset:4800
	ds_read_b128 v[212:215], v224 offset:9408
	ds_read_b128 v[216:219], v224 offset:14016
	s_waitcnt lgkmcnt(4)
	v_mfma_f32_16x16x32_bf16 v[188:191], v[118:121], v[78:81], v[188:191]
	v_mfma_f32_16x16x32_bf16 v[192:195], v[122:125], v[78:81], v[192:195]
	v_mfma_f32_16x16x32_bf16 v[196:199], v[126:129], v[78:81], v[196:199]
	v_mfma_f32_16x16x32_bf16 v[200:203], v[130:133], v[78:81], v[200:203]
	s_waitcnt lgkmcnt(0)
	v_mfma_f32_16x16x32_bf16 v[188:191], v[204:207], v[82:85], v[188:191]
	v_mfma_f32_16x16x32_bf16 v[192:195], v[208:211], v[82:85], v[192:195]
	v_mfma_f32_16x16x32_bf16 v[196:199], v[212:215], v[82:85], v[196:199]
	v_mfma_f32_16x16x32_bf16 v[200:203], v[216:219], v[82:85], v[200:203]
	ds_read_b64_tr_b16 v[118:119], v225 offset:18432
	ds_read_b64_tr_b16 v[120:121], v225 offset:23040
	ds_read_b64_tr_b16 v[122:123], v225 offset:18464
	ds_read_b64_tr_b16 v[124:125], v225 offset:23072
	ds_read_b64_tr_b16 v[126:127], v225 offset:18496
	ds_read_b64_tr_b16 v[128:129], v225 offset:23104
	ds_read_b64_tr_b16 v[130:131], v225 offset:18528
	ds_read_b64_tr_b16 v[132:133], v225 offset:23136
	v_max3_f32 v226, v188, v189, v190
	v_max3_f32 v227, v191, v192, v193
	v_max3_f32 v226, v226, v194, v195
	v_max3_f32 v227, v227, v196, v197
	v_max3_f32 v226, v226, v198, v199
	v_max3_f32 v227, v227, v200, v201
	v_max3_f32 v226, v226, v202, v203
	v_max_f32_e32 v226, v226, v227
	v_cmp_lt_f32_e32 vcc, 0x41000000, v226
	s_cbranch_vccnz .Lft_rescale_slcA

.Lft_done_slcA:
	s_cmp_lg_u64 s[70:71], 0
	s_cbranch_scc0 .Las_s3
	ds_read_b128 v[118:121], v224 offset:0
	ds_read_b128 v[122:125], v224 offset:4608
	ds_read_b128 v[126:129], v224 offset:9216
	ds_read_b128 v[130:133], v224 offset:13824
	ds_read_b128 v[204:207], v224 offset:64
	ds_read_b128 v[208:211], v224 offset:4672
	ds_read_b128 v[212:215], v224 offset:9280
	ds_read_b128 v[216:219], v224 offset:13888
	v_cndmask_b32_e64 v228, v66, v146, s[8:9]
	v_cndmask_b32_e64 v229, v67, v147, s[8:9]
	v_and_b32_e32 v228, s56, v228
	v_and_b32_e32 v229, s57, v229
	v_cmp_ne_u64_e32 vcc, 0, v[228:229]
	s_nop 1
	v_cndmask_b32_e32 v220, v165, v185, vcc
	v_xor_b32_e32 v220, 0x80000000, v220
	v_mov_b32_e32 v221, v220
	v_mov_b32_e32 v222, v220
	v_mov_b32_e32 v223, v220
	s_waitcnt lgkmcnt(4)
	s_nop 0
	v_mfma_f32_16x16x32_bf16 v[188:191], v[118:121], v[86:89], v[220:223]
	v_mfma_f32_16x16x32_bf16 v[192:195], v[122:125], v[86:89], v[220:223]
	v_mfma_f32_16x16x32_bf16 v[196:199], v[126:129], v[86:89], v[220:223]
	v_mfma_f32_16x16x32_bf16 v[200:203], v[130:133], v[86:89], v[220:223]
	ds_read_b128 v[118:121], v224 offset:128
	ds_read_b128 v[122:125], v224 offset:4736
	ds_read_b128 v[126:129], v224 offset:9344
	ds_read_b128 v[130:133], v224 offset:13952
	s_waitcnt lgkmcnt(4)
	v_mfma_f32_16x16x32_bf16 v[188:191], v[204:207], v[90:93], v[188:191]
	v_mfma_f32_16x16x32_bf16 v[192:195], v[208:211], v[90:93], v[192:195]
	v_mfma_f32_16x16x32_bf16 v[196:199], v[212:215], v[90:93], v[196:199]
	v_mfma_f32_16x16x32_bf16 v[200:203], v[216:219], v[90:93], v[200:203]
	ds_read_b128 v[204:207], v224 offset:192
	ds_read_b128 v[208:211], v224 offset:4800
	ds_read_b128 v[212:215], v224 offset:9408
	ds_read_b128 v[216:219], v224 offset:14016
	s_waitcnt lgkmcnt(4)
	v_mfma_f32_16x16x32_bf16 v[188:191], v[118:121], v[94:97], v[188:191]
	v_mfma_f32_16x16x32_bf16 v[192:195], v[122:125], v[94:97], v[192:195]
	v_mfma_f32_16x16x32_bf16 v[196:199], v[126:129], v[94:97], v[196:199]
	v_mfma_f32_16x16x32_bf16 v[200:203], v[130:133], v[94:97], v[200:203]
	s_waitcnt lgkmcnt(0)
	v_mfma_f32_16x16x32_bf16 v[188:191], v[204:207], v[98:101], v[188:191]
	v_mfma_f32_16x16x32_bf16 v[192:195], v[208:211], v[98:101], v[192:195]
	v_mfma_f32_16x16x32_bf16 v[196:199], v[212:215], v[98:101], v[196:199]
	v_mfma_f32_16x16x32_bf16 v[200:203], v[216:219], v[98:101], v[200:203]
	ds_read_b64_tr_b16 v[118:119], v225 offset:18432
	ds_read_b64_tr_b16 v[120:121], v225 offset:23040
	ds_read_b64_tr_b16 v[122:123], v225 offset:18464
	ds_read_b64_tr_b16 v[124:125], v225 offset:23072
	ds_read_b64_tr_b16 v[126:127], v225 offset:18496
	ds_read_b64_tr_b16 v[128:129], v225 offset:23104
	ds_read_b64_tr_b16 v[130:131], v225 offset:18528
	ds_read_b64_tr_b16 v[132:133], v225 offset:23136
	v_max3_f32 v226, v188, v189, v190
	v_max3_f32 v227, v191, v192, v193
	v_max3_f32 v226, v226, v194, v195
	v_max3_f32 v227, v227, v196, v197
	v_max3_f32 v226, v226, v198, v199
	v_max3_f32 v227, v227, v200, v201
	v_max3_f32 v226, v226, v202, v203
	v_max_f32_e32 v226, v226, v227
	v_cmp_lt_f32_e32 vcc, 0x41000000, v226
	s_cbranch_vccnz .Lft_rescale_slcB

.Las_s3:
	s_waitcnt lgkmcnt(0)
	s_mov_b64 exec, 1
	ds_add_u32 v231, v230 offset:512
	s_mov_b64 exec, -1
	s_add_i32 s54, s54, 1
	s_add_i32 s18, s18, 64
	v_lshl_add_u64 v[152:153], v[152:153], 0, s[20:21]
	v_lshl_add_u64 v[154:155], v[154:155], 0, s[20:21]
	v_add_u32_e32 v231, 4, v231
	s_mov_b32 s74, s75
	s_add_i32 s75, s75, 0x9000
	s_cmp_eq_u32 s75, 0x1b000
	s_cselect_b32 s75, 0, s75
	s_cmp_le_u32 s54, s46
	s_cbranch_scc1 .Las_loop
	s_waitcnt lgkmcnt(0)
	s_barrier
	s_branch .LBB0_1530
